# final RMSNorm: gain loads of all four quarters issued up front (no per-quarter load-wait ladder)
# baseline (speedup 1.0000x reference)
; __device__ __forceinline__ int opaque_tid() { int t = threadIdx.x; asm volatile("" : "+v"(t)); return t; }
; __device__ __forceinline__ int opaque_bid() { int t = blockIdx.x; asm volatile("" : "+s"(t)); return t; }
; __device__ __forceinline__ int opaque_gdim() { int t = gridDim.x; asm volatile("" : "+s"(t)); return t; }
; __device__ void final_norm_phase(float* H, const float* g) {
;     const int tid_ = opaque_tid(); const int lane = tid_ & 63, gw = opaque_bid() * 8 + (tid_ >> 6), nw = opaque_gdim() * 8;
;     for (int row = gw; row < RL; row += nw) {
;         float* sp = H + (size_t)row * 1024; f32x4 v[4]; float ss = 0.f;
; #pragma unroll
;         for (int j = 0; j < 4; ++j) { v[j] = *(const f32x4*)(sp + 256 * j + 4 * lane); ss += v[j][0] * v[j][0] + v[j][1] * v[j][1] + v[j][2] * v[j][2] + v[j][3] * v[j][3]; }
;         ss = wave_sum(ss);
;         const float rstd = rsqrtf(ss * (1.0f / 1024.0f) + NEPS);
; #pragma unroll
;         for (int j = 0; j < 4; ++j) { const f32x4 gg = *(const f32x4*)(g + 256 * j + 4 * lane); *(f32x4*)(sp + 256 * j + 4 * lane) = v[j] * rstd * gg; }
;     }
.LBB0_850:
	global_load_dwordx4 v[8:11], v[6:7], off offset:-3072
	global_load_dwordx4 v[12:15], v[6:7], off offset:-2048
	global_load_dwordx4 v[16:19], v[6:7], off offset:-1024
	global_load_dwordx4 v[20:23], v[6:7], off
	v_mov_b32_e32 v1, v220
	v_mov_b32_e32 v3, v220
	v_mov_b32_e32 v44, v220
	v_mov_b32_e32 v45, v220
	v_mov_b32_e32 v46, v220
	v_mov_b32_e32 v47, v220
	global_load_dwordx4 v[24:27], v[4:5], off
	global_load_dwordx4 v[60:63], v[4:5], off offset:1024
	global_load_dwordx4 v[64:67], v[4:5], off offset:2048
	global_load_dwordx4 v[68:71], v[4:5], off offset:3072
	v_lshlrev_b32_e32 v1, 2, v1
	v_xor_b32_e32 v1, 0x80, v1
	v_lshlrev_b32_e32 v3, 2, v3
	v_xor_b32_e32 v3, 64, v3
	v_add_u32_e32 v2, s4, v2
	s_waitcnt vmcnt(7)
	v_mov_b32_e32 v30, v9
	s_waitcnt vmcnt(6)
	v_mov_b32_e32 v31, v13
	v_mov_b32_e32 v28, v8
	v_mov_b32_e32 v29, v12
	s_waitcnt vmcnt(5)
	v_mov_b32_e32 v38, v17
	s_waitcnt vmcnt(4)
	v_mov_b32_e32 v39, v21
	v_pk_mul_f32 v[30:31], v[30:31], v[30:31]
	v_mov_b32_e32 v32, v10
	v_mov_b32_e32 v33, v14
	v_mov_b32_e32 v36, v16
	v_mov_b32_e32 v37, v20
	v_pk_mul_f32 v[38:39], v[38:39], v[38:39]
	v_pk_fma_f32 v[28:29], v[28:29], v[28:29], v[30:31]
	v_mov_b32_e32 v34, v11
	v_mov_b32_e32 v35, v15
	v_mov_b32_e32 v40, v18
	v_mov_b32_e32 v41, v22
	v_pk_fma_f32 v[30:31], v[36:37], v[36:37], v[38:39]
	v_pk_fma_f32 v[28:29], v[32:33], v[32:33], v[28:29]
	v_mov_b32_e32 v42, v19
	v_mov_b32_e32 v43, v23
	v_pk_fma_f32 v[30:31], v[40:41], v[40:41], v[30:31]
	v_pk_fma_f32 v[28:29], v[34:35], v[34:35], v[28:29]
	v_pk_fma_f32 v[30:31], v[42:43], v[42:43], v[30:31]
	v_add_f32_e32 v28, v28, v29
	v_add_f32_e32 v28, v28, v30
	v_add_f32_e32 v28, v28, v31
	ds_bpermute_b32 v1, v1, v28
	s_waitcnt lgkmcnt(0)
	v_add_f32_e32 v1, v28, v1
	ds_bpermute_b32 v3, v3, v1
	v_lshlrev_b32_e32 v28, 2, v44
	v_xor_b32_e32 v28, 32, v28
	s_waitcnt lgkmcnt(0)
	v_add_f32_e32 v1, v1, v3
	ds_bpermute_b32 v3, v28, v1
	v_lshlrev_b32_e32 v28, 2, v45
	v_xor_b32_e32 v28, 16, v28
	s_waitcnt lgkmcnt(0)
	v_add_f32_e32 v1, v1, v3
	ds_bpermute_b32 v3, v28, v1
	v_lshlrev_b32_e32 v28, 2, v46
	v_xor_b32_e32 v28, 8, v28
	s_waitcnt lgkmcnt(0)
	v_add_f32_e32 v1, v1, v3
	ds_bpermute_b32 v3, v28, v1
	v_lshlrev_b32_e32 v28, 2, v47
	v_xor_b32_e32 v28, 4, v28
	s_waitcnt lgkmcnt(0)
	v_add_f32_e32 v1, v1, v3
	ds_bpermute_b32 v3, v28, v1
	s_waitcnt lgkmcnt(0)
	v_add_f32_e32 v1, v1, v3
	v_fmamk_f32 v1, v1, 0x3a800000, v188
	v_mul_f32_e32 v3, 0x4b800000, v1
	v_cmp_gt_f32_e32 vcc, s44, v1
	s_nop 1
	v_cndmask_b32_e32 v1, v1, v3, vcc
	v_rsq_f32_e32 v1, v1
	s_nop 0
	v_mul_f32_e32 v3, 0x45800000, v1
	v_cndmask_b32_e32 v28, v1, v3, vcc
	v_pk_mul_f32 v[8:9], v[8:9], v[28:29] op_sel_hi:[1,0]
	v_pk_mul_f32 v[10:11], v[10:11], v[28:29] op_sel_hi:[1,0]
	s_waitcnt vmcnt(0)
	v_pk_mul_f32 v[8:9], v[24:25], v[8:9]
	v_pk_mul_f32 v[10:11], v[26:27], v[10:11]
	global_store_dwordx4 v[6:7], v[8:11], off offset:-3072
	v_pk_mul_f32 v[14:15], v[14:15], v[28:29] op_sel_hi:[1,0]
	v_pk_mul_f32 v[12:13], v[12:13], v[28:29] op_sel_hi:[1,0]
	v_cmp_lt_i32_e32 vcc, s57, v2
	s_or_b64 s[8:9], vcc, s[8:9]
	v_pk_mul_f32 v[8:9], v[60:61], v[12:13]
	v_pk_mul_f32 v[10:11], v[62:63], v[14:15]
	global_store_dwordx4 v[6:7], v[8:11], off offset:-2048
	v_pk_mul_f32 v[12:13], v[18:19], v[28:29] op_sel_hi:[1,0]
	v_pk_mul_f32 v[14:15], v[16:17], v[28:29] op_sel_hi:[1,0]
	s_nop 1
	v_pk_mul_f32 v[10:11], v[66:67], v[12:13]
	v_pk_mul_f32 v[8:9], v[64:65], v[14:15]
	global_store_dwordx4 v[6:7], v[8:11], off offset:-1024
	v_pk_mul_f32 v[12:13], v[22:23], v[28:29] op_sel_hi:[1,0]
	v_pk_mul_f32 v[14:15], v[20:21], v[28:29] op_sel_hi:[1,0]
	s_nop 1
	v_pk_mul_f32 v[10:11], v[70:71], v[12:13]
	v_pk_mul_f32 v[8:9], v[68:69], v[14:15]
	global_store_dwordx4 v[6:7], v[8:11], off
	v_lshl_add_u64 v[6:7], v[6:7], 0, s[6:7]
	s_andn2_b64 exec, exec, s[8:9]
	s_cbranch_execnz .LBB0_850
